# attention: no LDS drain before the tile barrier (waits moved to first consumer across the barrier), next tile's DMA address SALU moved before the barrier, next tile's first V fragments read before the
# speedup vs baseline: 1.0023x; 1.0023x over previous
; __device__ __forceinline__ float bflo(unsigned u) { return __uint_as_float(u << 16); }
; __device__ __forceinline__ float bfhi(unsigned u) { return __uint_as_float(u & 0xffff0000u); }
; #define DMA_WAIT_BAR() do { asm volatile("s_waitcnt vmcnt(0)" ::: "memory"); __syncthreads(); } while (0)
; #define RD_K(slot) do { const LAS unsigned char* kp_ = L + (slot) * ASLOT; \
;         _Pragma("unroll") for (int st = 0; st < 4; ++st) { kf[2 * st] = *(const LAS bf16x8*)(kp_ + (kb0 ^ (32 * st))); kf[2 * st + 1] = *(const LAS bf16x8*)(kp_ + 8192 + (kb0 ^ (32 * st))); } } while (0)
; __device__ __forceinline__ void attn_unit(LAS unsigned char* L, bf16_t* QKV, size_t rowbase, int S, int h, int qb, float lam, const float* subln, unsigned* kmax) {
;     ...
;     {
;         const int seq = rowbase < (size_t)TP ? (int)(rowbase >> 14) : 2 + (int)((rowbase - TP) >> 13);
;         unsigned* kp = kmax + (seq * 16 + 2 * h + hd) * 2;
;         const float kb = sqrtf(__uint_as_float(__hip_atomic_load(kp, __ATOMIC_RELAXED, __HIP_MEMORY_SCOPE_AGENT)) + __uint_as_float(__hip_atomic_load(kp + 1, __ATOMIC_RELAXED, __HIP_MEMORY_SCOPE_AGENT)));
;         float q2 = 0.f;
; #pragma unroll
;         for (int st = 0; st < 4; ++st) { const u32x4 w = __builtin_bit_cast(u32x4, qf[st]);
;             q2 += ((bflo(w.x) * bflo(w.x) + bfhi(w.x) * bfhi(w.x)) + (bflo(w.y) * bflo(w.y) + bfhi(w.y) * bfhi(w.y))) + ((bflo(w.z) * bflo(w.z) + bfhi(w.z) * bfhi(w.z)) + (bflo(w.w) * bflo(w.w) + bfhi(w.w) * bfhi(w.w))); }
;         q2 += __shfl_xor(q2, 32);
;         const float mref = sqrtf(q2) * kb;
; #pragma unroll
;         for (int r = 0; r < 16; ++r) negm[r] = -mref; }
;     DMA_WAIT_BAR();
;     bf16x8 kf[8], va[4], vb[4];
;     ...
;     RD_K(0);
;     __syncthreads();
.LBB0_926:
	s_lshl_b32 s5, s63, 2
	s_lshl_b32 s10, s40, 1
	s_lshl_b32 s4, s22, 5
	s_add_i32 s5, s10, s5
	s_add_i32 s10, s5, s4
	s_lshl_b32 s23, s40, 3
	s_lshl_b64 s[4:5], s[10:11], 2
	s_add_u32 s4, s26, s4
	s_addc_u32 s5, s27, s5
	global_load_dword v25, v157, s[4:5] sc1
	global_load_dword v27, v157, s[4:5] offset:4 sc1
	s_waitcnt vmcnt(5)
	v_and_b32_e32 v3, 0xffff0000, v113
	v_and_b32_e32 v2, 0xffff0000, v112
	v_and_b32_e32 v7, 0xffff0000, v115
	v_and_b32_e32 v6, 0xffff0000, v114
	s_waitcnt vmcnt(4)
	v_and_b32_e32 v11, 0xffff0000, v117
	v_and_b32_e32 v10, 0xffff0000, v116
	v_and_b32_e32 v15, 0xffff0000, v119
	v_and_b32_e32 v14, 0xffff0000, v118
	v_lshlrev_b32_e32 v1, 16, v113
	v_lshlrev_b32_e32 v0, 16, v112
	v_lshlrev_b32_e32 v5, 16, v115
	v_lshlrev_b32_e32 v4, 16, v114
	v_lshlrev_b32_e32 v9, 16, v117
	v_lshlrev_b32_e32 v8, 16, v116
	v_lshlrev_b32_e32 v13, 16, v119
	v_lshlrev_b32_e32 v12, 16, v118
	v_pk_mul_f32 v[2:3], v[2:3], v[2:3]
	v_pk_mul_f32 v[6:7], v[6:7], v[6:7]
	v_pk_mul_f32 v[10:11], v[10:11], v[10:11]
	v_pk_mul_f32 v[14:15], v[14:15], v[14:15]
	s_waitcnt vmcnt(2)
	v_lshlrev_b32_e32 v24, 16, v124
	v_and_b32_e32 v26, 0xffff0000, v124
	v_lshlrev_b32_e32 v28, 16, v125
	v_and_b32_e32 v29, 0xffff0000, v125
	v_pk_fma_f32 v[0:1], v[0:1], v[0:1], v[2:3]
	v_pk_fma_f32 v[2:3], v[4:5], v[4:5], v[6:7]
	v_pk_fma_f32 v[4:5], v[8:9], v[8:9], v[10:11]
	v_pk_fma_f32 v[6:7], v[12:13], v[12:13], v[14:15]
	v_mul_f32_e32 v35, v24, v24
	v_mul_f32_e32 v36, v26, v26
	v_mul_f32_e32 v37, v28, v28
	v_mul_f32_e32 v29, v29, v29
	v_pk_add_f32 v[0:1], v[0:1], v[0:1] op_sel:[0,1] op_sel_hi:[1,0]
	v_pk_add_f32 v[2:3], v[2:3], v[2:3] op_sel:[0,1] op_sel_hi:[1,0]
	v_pk_add_f32 v[4:5], v[4:5], v[4:5] op_sel:[0,1] op_sel_hi:[1,0]
	v_pk_add_f32 v[6:7], v[6:7], v[6:7] op_sel:[0,1] op_sel_hi:[1,0]
	v_mov_b32_e32 v1, v35
	v_mov_b32_e32 v3, v36
	v_mov_b32_e32 v5, v37
	v_mov_b32_e32 v7, v29
	v_pk_add_f32 v[0:1], v[0:1], v[2:3]
	v_pk_add_f32 v[2:3], v[4:5], v[6:7]
	v_and_b32_e32 v17, 0xffff0000, v120
	v_and_b32_e32 v19, 0xffff0000, v121
	v_and_b32_e32 v21, 0xffff0000, v122
	v_and_b32_e32 v23, 0xffff0000, v123
	v_lshlrev_b32_e32 v30, 16, v126
	v_and_b32_e32 v31, 0xffff0000, v126
	v_pk_add_f32 v[0:1], v[0:1], v[2:3]
	v_lshlrev_b32_e32 v16, 16, v120
	v_lshlrev_b32_e32 v18, 16, v121
	v_lshlrev_b32_e32 v20, 16, v122
	v_lshlrev_b32_e32 v22, 16, v123
	v_lshlrev_b32_e32 v32, 16, v127
	v_and_b32_e32 v33, 0xffff0000, v127
	v_mul_f32_e32 v38, v30, v30
	v_mul_f32_e32 v31, v31, v31
	v_mul_f32_e32 v24, v17, v17
	v_mul_f32_e32 v26, v19, v19
	v_mul_f32_e32 v28, v21, v21
	v_mul_f32_e32 v30, v23, v23
	v_mul_f32_e32 v32, v32, v32
	v_mul_f32_e32 v33, v33, v33
	v_pk_fma_f32 v[12:13], v[20:21], v[20:21], v[28:29] op_sel_hi:[1,1,0]
	v_pk_fma_f32 v[14:15], v[22:23], v[22:23], v[30:31] op_sel_hi:[1,1,0]
	v_mov_b32_e32 v13, v32
	v_mov_b32_e32 v15, v33
	v_and_b32_e32 v6, 64, v186
	v_add_u32_e32 v6, 64, v6
	v_bitop3_b32 v34, s23, v171, v181 bitop3:0x36
	v_lshl_add_u32 v34, v34, 4, v172
	v_add_u32_e32 v188, 0, v34
	s_waitcnt vmcnt(0)
	s_barrier
	ds_read_b128 v[80:83], v188
	ds_read_b128 v[128:131], v188 offset:8192
	v_mov_b32_e32 v187, 0
	s_waitcnt vmcnt(1)
	v_pk_fma_f32 v[8:9], v[16:17], v[16:17], v[24:25] op_sel_hi:[1,1,0]
	s_waitcnt vmcnt(0)
	v_add_f32_e32 v2, v27, v25
	v_mul_f32_e32 v3, 0x4f800000, v2
	v_cmp_gt_f32_e32 vcc, s37, v2
	v_pk_fma_f32 v[10:11], v[18:19], v[18:19], v[26:27] op_sel_hi:[1,1,0]
	v_mov_b32_e32 v9, v38
	v_cndmask_b32_e32 v4, v2, v3, vcc
	v_mov_b32_e32 v11, v31
	v_sqrt_f32_e32 v5, v4
	v_pk_add_f32 v[8:9], v[8:9], v[10:11]
	v_pk_add_f32 v[10:11], v[12:13], v[14:15]
	s_add_i32 s24, s42, -1
	v_pk_add_f32 v[2:3], v[8:9], v[10:11]
	s_add_i32 s25, s43, 0x1c000
	v_pk_add_f32 v[0:1], v[0:1], v[2:3]
	v_xor_b32_e32 v3, 32, v186
	v_add_f32_e32 v0, v0, v1
	v_add_u32_e32 v1, -1, v5
	v_fma_f32 v2, -v1, v5, v4
	v_cmp_ge_f32_e64 s[4:5], 0, v2
	v_add_u32_e32 v2, 1, v5
	s_add_i32 s63, s43, 0x1e000
	v_cndmask_b32_e64 v1, v5, v1, s[4:5]
	v_cmp_lt_i32_e64 s[4:5], v3, v6
	v_fma_f32 v5, -v2, v5, v4
	s_mov_b32 s68, 7
	v_cndmask_b32_e64 v3, v186, v3, s[4:5]
	v_lshlrev_b32_e32 v156, 2, v3
	ds_bpermute_b32 v3, v156, v0
	v_cmp_lt_f32_e64 s[4:5], 0, v5
	v_mov_b32_e32 v192, 0
	v_mov_b32_e32 v193, 0
	v_cndmask_b32_e64 v1, v1, v2, s[4:5]
	s_waitcnt lgkmcnt(0)
; __device__ __forceinline__ float bflo(unsigned u) { return __uint_as_float(u << 16); }
; __device__ __forceinline__ float bfhi(unsigned u) { return __uint_as_float(u & 0xffff0000u); }
; #define DMA_WAIT_BAR() do { asm volatile("s_waitcnt vmcnt(0)" ::: "memory"); __syncthreads(); } while (0)
; #define RD_K(slot) do { const LAS unsigned char* kp_ = L + (slot) * ASLOT; \
;         _Pragma("unroll") for (int st = 0; st < 4; ++st) { kf[2 * st] = *(const LAS bf16x8*)(kp_ + (kb0 ^ (32 * st))); kf[2 * st + 1] = *(const LAS bf16x8*)(kp_ + 8192 + (kb0 ^ (32 * st))); } } while (0)
; __device__ __forceinline__ void attn_unit(LAS unsigned char* L, bf16_t* QKV, size_t rowbase, int S, int h, int qb, float lam, const float* subln, unsigned* kmax) {
;     ...
;     f32x16 o[4], negm; float lsum = 0.f, lsb = 0.f, lsc = 0.f, lsd = 0.f;
; #pragma unroll
;     for (int d = 0; d < 4; ++d) o[d] = (f32x16){};
;     {
;         const int seq = rowbase < (size_t)TP ? (int)(rowbase >> 14) : 2 + (int)((rowbase - TP) >> 13);
;         unsigned* kp = kmax + (seq * 16 + 2 * h + hd) * 2;
;         const float kb = sqrtf(__uint_as_float(__hip_atomic_load(kp, __ATOMIC_RELAXED, __HIP_MEMORY_SCOPE_AGENT)) + __uint_as_float(__hip_atomic_load(kp + 1, __ATOMIC_RELAXED, __HIP_MEMORY_SCOPE_AGENT)));
;         float q2 = 0.f;
; #pragma unroll
;         for (int st = 0; st < 4; ++st) { const u32x4 w = __builtin_bit_cast(u32x4, qf[st]);
;             q2 += ((bflo(w.x) * bflo(w.x) + bfhi(w.x) * bfhi(w.x)) + (bflo(w.y) * bflo(w.y) + bfhi(w.y) * bfhi(w.y))) + ((bflo(w.z) * bflo(w.z) + bfhi(w.z) * bfhi(w.z)) + (bflo(w.w) * bflo(w.w) + bfhi(w.w) * bfhi(w.w))); }
;         q2 += __shfl_xor(q2, 32);
;         const float mref = sqrtf(q2) * kb;
; #pragma unroll
;         for (int r = 0; r < 16; ++r) negm[r] = -mref; }
;     DMA_WAIT_BAR();
;     bf16x8 kf[8], va[4], vb[4];
;     ...
;     RD_K(0);
;     __syncthreads();
;     bf16x8 pf[4];
	v_add_f32_e32 v0, v0, v3
	v_mul_f32_e32 v3, 0x4f800000, v0
	v_cmp_gt_f32_e64 s[4:5], s37, v0
	v_mul_f32_e32 v2, 0x37800000, v1
	v_cndmask_b32_e32 v1, v1, v2, vcc
	v_cndmask_b32_e64 v0, v0, v3, s[4:5]
	v_sqrt_f32_e32 v3, v0
	v_cmp_class_f32_e32 vcc, v4, v173
	v_mov_b32_e32 v194, 0
	v_mov_b32_e32 v5, v187
	v_add_u32_e32 v2, -1, v3
	v_cndmask_b32_e32 v1, v1, v4, vcc
	v_fma_f32 v4, -v2, v3, v0
	v_cmp_ge_f32_e32 vcc, 0, v4
	v_add_u32_e32 v4, 1, v3
	v_mov_b32_e32 v6, v187
	v_cndmask_b32_e32 v2, v3, v2, vcc
	v_fma_f32 v3, -v4, v3, v0
	v_cmp_lt_f32_e32 vcc, 0, v3
	v_mov_b32_e32 v7, v187
	v_mov_b32_e32 v8, v187
	v_cndmask_b32_e32 v2, v2, v4, vcc
	v_mul_f32_e32 v3, 0x37800000, v2
	v_cndmask_b32_e64 v2, v2, v3, s[4:5]
	v_cmp_class_f32_e32 vcc, v0, v173
	v_mov_b32_e32 v3, v187
	v_mov_b32_e32 v4, v187
	v_cndmask_b32_e32 v0, v2, v0, vcc
	v_mul_f32_e64 v64, v0, -v1
	v_xor_b32_e32 v0, 32, v34
	v_add_u32_e32 v189, 0, v0
	v_xor_b32_e32 v0, 64, v34
	v_add_u32_e32 v190, 0, v0
	v_xor_b32_e32 v0, 0x60, v34
	v_add_u32_e32 v191, 0, v0
	ds_read_b128 v[132:135], v189
	ds_read_b128 v[136:139], v189 offset:8192
	ds_read_b128 v[140:143], v190
	ds_read_b128 v[144:147], v190 offset:8192
	ds_read_b128 v[148:151], v191
	ds_read_b128 v[152:155], v191 offset:8192
	v_mov_b32_e32 v65, v64
	v_mov_b32_e32 v66, v64
	v_mov_b32_e32 v67, v64
	v_mov_b32_e32 v68, v64
	v_mov_b32_e32 v69, v64
	v_mov_b32_e32 v70, v64
	v_mov_b32_e32 v71, v64
	v_mov_b32_e32 v72, v64
	v_mov_b32_e32 v73, v64
	v_mov_b32_e32 v74, v64
	v_mov_b32_e32 v75, v64
	v_mov_b32_e32 v76, v64
	v_mov_b32_e32 v77, v64
	v_mov_b32_e32 v78, v64
	v_mov_b32_e32 v79, v64
	v_mov_b32_e32 v0, 0
	v_mov_b32_e32 v1, v187
	v_mov_b32_e32 v2, v187
	v_mov_b32_e32 v9, v187
	v_mov_b32_e32 v10, v187
	v_mov_b32_e32 v11, v187
	v_mov_b32_e32 v12, v187
	v_mov_b32_e32 v13, v187
	v_mov_b32_e32 v14, v187
	v_mov_b32_e32 v15, v187
	v_mov_b32_e32 v16, 0
	v_mov_b32_e32 v17, v187
	v_mov_b32_e32 v18, v187
	v_mov_b32_e32 v19, v187
	v_mov_b32_e32 v20, v187
	v_mov_b32_e32 v21, v187
	v_mov_b32_e32 v22, v187
	v_mov_b32_e32 v23, v187
	v_mov_b32_e32 v24, v187
	v_mov_b32_e32 v25, v187
	v_mov_b32_e32 v26, v187
	v_mov_b32_e32 v27, v187
	v_mov_b32_e32 v28, v187
	v_mov_b32_e32 v29, v187
	v_mov_b32_e32 v30, v187
	v_mov_b32_e32 v31, v187
	v_mov_b32_e32 v32, 0
	v_mov_b32_e32 v33, v187
	v_mov_b32_e32 v34, v187
	v_mov_b32_e32 v35, v187
	v_mov_b32_e32 v36, v187
	v_mov_b32_e32 v37, v187
	v_mov_b32_e32 v38, v187
	v_mov_b32_e32 v39, v187
	v_mov_b32_e32 v40, v187
	v_mov_b32_e32 v41, v187
	v_mov_b32_e32 v42, v187
	v_mov_b32_e32 v43, v187
	v_mov_b32_e32 v44, v187
	v_mov_b32_e32 v45, v187
	v_mov_b32_e32 v46, v187
	v_mov_b32_e32 v47, v187
	v_mov_b32_e32 v48, 0
	v_mov_b32_e32 v49, v187
	v_mov_b32_e32 v50, v187
	v_mov_b32_e32 v51, v187
	v_mov_b32_e32 v52, v187
	v_mov_b32_e32 v53, v187
	v_mov_b32_e32 v54, v187
	v_mov_b32_e32 v55, v187
	v_mov_b32_e32 v56, v187
	v_mov_b32_e32 v57, v187
	v_mov_b32_e32 v58, v187
	v_mov_b32_e32 v59, v187
	v_mov_b32_e32 v60, v187
	v_mov_b32_e32 v61, v187
	v_mov_b32_e32 v62, v187
	v_mov_b32_e32 v63, v187
	s_add_u32 s22, s20, 0x10000
	s_addc_u32 s23, s21, 0
	s_add_u32 s4, s20, 0x18000
	s_addc_u32 s5, s21, 0
	ds_read_b64_tr_b16 v[224:225], v174
	ds_read_b64_tr_b16 v[226:227], v175 offset:2048
	ds_read_b64_tr_b16 v[228:229], v176
	ds_read_b64_tr_b16 v[230:231], v177 offset:2048
	ds_read_b64_tr_b16 v[232:233], v178
	ds_read_b64_tr_b16 v[234:235], v179 offset:2048
	ds_read_b64_tr_b16 v[236:237], v183
	ds_read_b64_tr_b16 v[238:239], v184 offset:2048
	v_add_u32_e32 v254, 0x4000, v163
	v_add_u32_e32 v255, 0x100, v163
	v_add_u32_e32 v253, 0x4100, v163
	s_waitcnt lgkmcnt(0)
	s_barrier
.LBB0_927:
	s_add_i32 s69, s68, -3
	s_mov_b32 m0, s53
	v_mfma_f32_32x32x16_bf16 v[96:111], v[132:135], v[116:119], v[64:79]
	global_load_lds_dwordx4 v163, s[4:5]
	s_mov_b32 m0, s58
	v_mfma_f32_32x32x16_bf16 v[96:111], v[140:143], v[120:123], v[96:111]
	global_load_lds_dwordx4 v254, s[4:5]
	s_mov_b32 m0, s25
	s_waitcnt lgkmcnt(10)
	v_mfma_f32_32x32x16_bf16 v[96:111], v[148:151], v[124:127], v[96:111]
	global_load_lds_dwordx4 v255, s[4:5]
	ds_read_b64_tr_b16 v[132:133], v176 offset:4096
	ds_read_b64_tr_b16 v[134:135], v177 offset:6144
	s_mov_b32 m0, s63
	s_waitcnt lgkmcnt(10)
	v_mfma_f32_32x32x16_bf16 v[96:111], v[80:83], v[112:115], v[96:111]
	global_load_lds_dwordx4 v253, s[4:5]
	ds_read_b64_tr_b16 v[140:141], v183 offset:4096
	ds_read_b64_tr_b16 v[142:143], v184 offset:6144
	v_mfma_f32_32x32x16_bf16 v[80:95], v[128:131], v[112:115], v[64:79]
	ds_read_b64_tr_b16 v[128:129], v174 offset:4096
	ds_read_b64_tr_b16 v[130:131], v175 offset:6144
	v_mfma_f32_32x32x16_bf16 v[80:95], v[136:139], v[116:119], v[80:95]
	s_nop 3
	v_mfma_f32_32x32x16_bf16 v[80:95], v[144:147], v[120:123], v[80:95]
	v_exp_f32_e32 v96, v96
	v_exp_f32_e32 v97, v97
	v_exp_f32_e32 v98, v98
	v_mfma_f32_32x32x16_bf16 v[80:95], v[152:155], v[124:127], v[80:95]
	v_exp_f32_e32 v99, v99
	v_exp_f32_e32 v100, v100
	v_exp_f32_e32 v101, v101
	v_exp_f32_e32 v102, v102
	v_exp_f32_e32 v103, v103
	v_cvt_pk_bf16_f32 v208, v96, v97
	v_cvt_pk_bf16_f32 v209, v98, v99
	v_cvt_pk_bf16_f32 v210, v100, v101
	v_cvt_pk_bf16_f32 v211, v102, v103
	v_exp_f32_e32 v104, v104
	v_exp_f32_e32 v105, v105
	s_waitcnt lgkmcnt(6)
	v_mfma_f32_32x32x16_bf16 v[48:63], v[224:227], v[208:211], v[48:63]
	v_exp_f32_e32 v106, v106
	v_exp_f32_e32 v107, v107
	v_exp_f32_e32 v108, v108
	ds_read_b64_tr_b16 v[136:137], v178 offset:4096
	ds_read_b64_tr_b16 v[138:139], v179 offset:6144
	v_mfma_f32_32x32x16_bf16 v[32:47], v[228:231], v[208:211], v[32:47]
	v_exp_f32_e32 v109, v109
	v_exp_f32_e32 v110, v110
	v_exp_f32_e32 v111, v111
	ds_read_b64_tr_b16 v[144:145], v174 offset:8192
	ds_read_b64_tr_b16 v[146:147], v175 offset:10240
	v_mfma_f32_32x32x16_bf16 v[16:31], v[232:235], v[208:211], v[16:31]
	v_cvt_pk_bf16_f32 v212, v104, v105
	v_cvt_pk_bf16_f32 v213, v106, v107
	v_cvt_pk_bf16_f32 v214, v108, v109
	v_cvt_pk_bf16_f32 v215, v110, v111
	v_add_f32_e32 v187, v96, v187
	v_add_f32_e32 v192, v97, v192
	ds_read_b64_tr_b16 v[148:149], v176 offset:8192
	ds_read_b64_tr_b16 v[150:151], v177 offset:10240
	v_mfma_f32_32x32x16_bf16 v[0:15], v[236:239], v[208:211], v[0:15]
	v_add_f32_e32 v193, v98, v193
	v_add_f32_e32 v194, v99, v194
	v_add_f32_e32 v187, v100, v187
	v_add_f32_e32 v192, v101, v192
	v_add_f32_e32 v193, v102, v193
	v_add_f32_e32 v194, v103, v194
	ds_read_b64_tr_b16 v[152:153], v178 offset:8192
	ds_read_b64_tr_b16 v[154:155], v179 offset:10240
	s_waitcnt lgkmcnt(6)
	v_mfma_f32_32x32x16_bf16 v[48:63], v[128:131], v[212:215], v[48:63]
	v_exp_f32_e32 v80, v80
	v_exp_f32_e32 v81, v81
	v_exp_f32_e32 v82, v82
	ds_read_b64_tr_b16 v[240:241], v183 offset:8192
	ds_read_b64_tr_b16 v[242:243], v184 offset:10240
	ds_read_b128 v[128:131], v188 offset:24576
	v_mfma_f32_32x32x16_bf16 v[32:47], v[132:135], v[212:215], v[32:47]
	v_exp_f32_e32 v83, v83
	v_exp_f32_e32 v84, v84
	v_exp_f32_e32 v85, v85
	ds_read_b64_tr_b16 v[196:197], v174 offset:12288
	ds_read_b64_tr_b16 v[198:199], v175 offset:14336
	ds_read_b128 v[132:135], v189 offset:16384
	v_mfma_f32_32x32x16_bf16 v[16:31], v[136:139], v[212:215], v[16:31]
	v_exp_f32_e32 v86, v86
	v_exp_f32_e32 v87, v87
	v_cvt_pk_bf16_f32 v216, v80, v81
	v_cvt_pk_bf16_f32 v217, v82, v83
	ds_read_b64_tr_b16 v[200:201], v176 offset:12288
	ds_read_b64_tr_b16 v[202:203], v177 offset:14336
	ds_read_b128 v[136:139], v189 offset:24576
	v_mfma_f32_32x32x16_bf16 v[0:15], v[140:143], v[212:215], v[0:15]
	v_cvt_pk_bf16_f32 v218, v84, v85
	v_cvt_pk_bf16_f32 v219, v86, v87
	v_add_f32_e32 v187, v104, v187
	v_add_f32_e32 v192, v105, v192
	v_add_f32_e32 v193, v106, v193
	v_add_f32_e32 v194, v107, v194
	s_waitcnt lgkmcnt(12)
	ds_read_b64_tr_b16 v[204:205], v178 offset:12288
	ds_read_b64_tr_b16 v[206:207], v179 offset:14336
	ds_read_b128 v[140:143], v190 offset:16384
	s_waitcnt lgkmcnt(10)
	v_mfma_f32_32x32x16_bf16 v[48:63], v[144:147], v[216:219], v[48:63]
	v_exp_f32_e32 v88, v88
	v_exp_f32_e32 v89, v89
	v_exp_f32_e32 v90, v90
	ds_read_b64_tr_b16 v[246:247], v183 offset:12288
	ds_read_b64_tr_b16 v[248:249], v184 offset:14336
	ds_read_b128 v[144:147], v190 offset:24576
	v_mfma_f32_32x32x16_bf16 v[32:47], v[148:151], v[216:219], v[32:47]
	v_exp_f32_e32 v91, v91
	v_exp_f32_e32 v92, v92
	v_exp_f32_e32 v93, v93
	ds_read_b128 v[148:151], v191 offset:16384
	v_mfma_f32_32x32x16_bf16 v[16:31], v[152:155], v[216:219], v[16:31]
	v_exp_f32_e32 v94, v94
	v_exp_f32_e32 v95, v95
	v_cvt_pk_bf16_f32 v220, v88, v89
	v_cvt_pk_bf16_f32 v221, v90, v91
	ds_read_b128 v[152:155], v191 offset:24576
	v_mfma_f32_32x32x16_bf16 v[0:15], v[240:243], v[216:219], v[0:15]
	v_cvt_pk_bf16_f32 v222, v92, v93
	v_cvt_pk_bf16_f32 v223, v94, v95
	v_add_f32_e32 v187, v80, v187
	v_add_f32_e32 v192, v81, v192
	v_add_f32_e32 v193, v82, v193
	v_add_f32_e32 v194, v83, v194
	s_waitcnt lgkmcnt(3)
	v_mfma_f32_32x32x16_bf16 v[48:63], v[196:199], v[220:223], v[48:63]
	v_add_f32_e32 v187, v108, v187
	v_add_f32_e32 v192, v109, v192
	v_add_f32_e32 v193, v110, v193
	v_add_f32_e32 v194, v111, v194
	v_add_f32_e32 v187, v84, v187
	v_add_f32_e32 v192, v85, v192
	ds_read_b128 v[80:83], v188 offset:16384
	ds_read_b64_tr_b16 v[224:225], v174 offset:16384
	ds_read_b64_tr_b16 v[226:227], v175 offset:18432
	v_mfma_f32_32x32x16_bf16 v[32:47], v[200:203], v[220:223], v[32:47]
	v_add_f32_e32 v193, v86, v193
	v_add_f32_e32 v194, v87, v194
	v_add_f32_e32 v187, v88, v187
	v_add_f32_e32 v192, v89, v192
	v_add_f32_e32 v193, v90, v193
	v_add_f32_e32 v194, v91, v194
	ds_read_b64_tr_b16 v[228:229], v176 offset:16384
	ds_read_b64_tr_b16 v[230:231], v177 offset:18432
	v_mfma_f32_32x32x16_bf16 v[16:31], v[204:207], v[220:223], v[16:31]
	v_add_f32_e32 v187, v92, v187
	v_add_f32_e32 v192, v93, v192
	v_add_f32_e32 v193, v94, v193
	v_add_f32_e32 v194, v95, v194
	ds_read_b64_tr_b16 v[232:233], v178 offset:16384
	ds_read_b64_tr_b16 v[234:235], v179 offset:18432
	v_mfma_f32_32x32x16_bf16 v[0:15], v[246:249], v[220:223], v[0:15]
	ds_read_b64_tr_b16 v[236:237], v183 offset:16384
	ds_read_b64_tr_b16 v[238:239], v184 offset:18432
	s_add_i32 s10, s68, -3
	s_min_u32 s10, s10, s24
	s_lshl_b32 s10, s10, 15
	s_add_u32 s22, s20, s10
	s_addc_u32 s23, s21, 0
	s_waitcnt vmcnt(4)
	s_barrier
; __device__ __forceinline__ void attn_unit(LAS unsigned char* L, bf16_t* QKV, size_t rowbase, int S, int h, int qb, float lam, const float* subln, unsigned* kmax) {
;     ...
;     for (int t = 0; t < NT; t += 4) { TILE(t, 0); TILE(t + 1, 1); TILE(t + 2, 2); TILE(t + 3, 3); }
	s_mov_b32 m0, s43
	v_mfma_f32_32x32x16_bf16 v[96:111], v[132:135], v[116:119], v[64:79]
	global_load_lds_dwordx4 v163, s[22:23]
	s_mov_b32 m0, s45
	v_mfma_f32_32x32x16_bf16 v[96:111], v[140:143], v[120:123], v[96:111]
	global_load_lds_dwordx4 v254, s[22:23]
	s_mov_b32 m0, s44
	s_waitcnt lgkmcnt(10)
	v_mfma_f32_32x32x16_bf16 v[96:111], v[148:151], v[124:127], v[96:111]
	global_load_lds_dwordx4 v255, s[22:23]
	ds_read_b64_tr_b16 v[132:133], v176 offset:20480
	ds_read_b64_tr_b16 v[134:135], v177 offset:22528
	s_mov_b32 m0, s48
	s_waitcnt lgkmcnt(10)
	v_mfma_f32_32x32x16_bf16 v[96:111], v[80:83], v[112:115], v[96:111]
	global_load_lds_dwordx4 v253, s[22:23]
	ds_read_b64_tr_b16 v[140:141], v183 offset:20480
	ds_read_b64_tr_b16 v[142:143], v184 offset:22528
	v_mfma_f32_32x32x16_bf16 v[80:95], v[128:131], v[112:115], v[64:79]
	ds_read_b64_tr_b16 v[128:129], v174 offset:20480
	ds_read_b64_tr_b16 v[130:131], v175 offset:22528
	v_mfma_f32_32x32x16_bf16 v[80:95], v[136:139], v[116:119], v[80:95]
	s_nop 3
	v_mfma_f32_32x32x16_bf16 v[80:95], v[144:147], v[120:123], v[80:95]
	v_exp_f32_e32 v96, v96
	v_exp_f32_e32 v97, v97
	v_exp_f32_e32 v98, v98
	v_mfma_f32_32x32x16_bf16 v[80:95], v[152:155], v[124:127], v[80:95]
	v_exp_f32_e32 v99, v99
	v_exp_f32_e32 v100, v100
	v_exp_f32_e32 v101, v101
	v_exp_f32_e32 v102, v102
	v_exp_f32_e32 v103, v103
	v_cvt_pk_bf16_f32 v208, v96, v97
	v_cvt_pk_bf16_f32 v209, v98, v99
	v_cvt_pk_bf16_f32 v210, v100, v101
	v_cvt_pk_bf16_f32 v211, v102, v103
	v_exp_f32_e32 v104, v104
	v_exp_f32_e32 v105, v105
	s_waitcnt lgkmcnt(6)
	v_mfma_f32_32x32x16_bf16 v[48:63], v[224:227], v[208:211], v[48:63]
	v_exp_f32_e32 v106, v106
	v_exp_f32_e32 v107, v107
	v_exp_f32_e32 v108, v108
	ds_read_b64_tr_b16 v[136:137], v178 offset:20480
	ds_read_b64_tr_b16 v[138:139], v179 offset:22528
	v_mfma_f32_32x32x16_bf16 v[32:47], v[228:231], v[208:211], v[32:47]
	v_exp_f32_e32 v109, v109
	v_exp_f32_e32 v110, v110
	v_exp_f32_e32 v111, v111
	ds_read_b64_tr_b16 v[144:145], v174 offset:24576
	ds_read_b64_tr_b16 v[146:147], v175 offset:26624
	v_mfma_f32_32x32x16_bf16 v[16:31], v[232:235], v[208:211], v[16:31]
	v_cvt_pk_bf16_f32 v212, v104, v105
	v_cvt_pk_bf16_f32 v213, v106, v107
	v_cvt_pk_bf16_f32 v214, v108, v109
	v_cvt_pk_bf16_f32 v215, v110, v111
	v_add_f32_e32 v187, v96, v187
	v_add_f32_e32 v192, v97, v192
	ds_read_b64_tr_b16 v[148:149], v176 offset:24576
	ds_read_b64_tr_b16 v[150:151], v177 offset:26624
	v_mfma_f32_32x32x16_bf16 v[0:15], v[236:239], v[208:211], v[0:15]
	v_add_f32_e32 v193, v98, v193
	v_add_f32_e32 v194, v99, v194
	v_add_f32_e32 v187, v100, v187
	v_add_f32_e32 v192, v101, v192
	v_add_f32_e32 v193, v102, v193
	v_add_f32_e32 v194, v103, v194
	ds_read_b64_tr_b16 v[152:153], v178 offset:24576
	ds_read_b64_tr_b16 v[154:155], v179 offset:26624
	s_waitcnt lgkmcnt(6)
	v_mfma_f32_32x32x16_bf16 v[48:63], v[128:131], v[212:215], v[48:63]
	v_exp_f32_e32 v80, v80
	v_exp_f32_e32 v81, v81
	v_exp_f32_e32 v82, v82
	ds_read_b64_tr_b16 v[240:241], v183 offset:24576
	ds_read_b64_tr_b16 v[242:243], v184 offset:26624
	ds_read_b128 v[128:131], v188 offset:40960
	v_mfma_f32_32x32x16_bf16 v[32:47], v[132:135], v[212:215], v[32:47]
	v_exp_f32_e32 v83, v83
	v_exp_f32_e32 v84, v84
	v_exp_f32_e32 v85, v85
	ds_read_b64_tr_b16 v[196:197], v174 offset:28672
	ds_read_b64_tr_b16 v[198:199], v175 offset:30720
	ds_read_b128 v[132:135], v189 offset:32768
	v_mfma_f32_32x32x16_bf16 v[16:31], v[136:139], v[212:215], v[16:31]
	v_exp_f32_e32 v86, v86
	v_exp_f32_e32 v87, v87
	v_cvt_pk_bf16_f32 v216, v80, v81
	v_cvt_pk_bf16_f32 v217, v82, v83
	ds_read_b64_tr_b16 v[200:201], v176 offset:28672
	ds_read_b64_tr_b16 v[202:203], v177 offset:30720
	ds_read_b128 v[136:139], v189 offset:40960
	v_mfma_f32_32x32x16_bf16 v[0:15], v[140:143], v[212:215], v[0:15]
	v_cvt_pk_bf16_f32 v218, v84, v85
	v_cvt_pk_bf16_f32 v219, v86, v87
	v_add_f32_e32 v187, v104, v187
	v_add_f32_e32 v192, v105, v192
	v_add_f32_e32 v193, v106, v193
	v_add_f32_e32 v194, v107, v194
	s_waitcnt lgkmcnt(12)
	ds_read_b64_tr_b16 v[204:205], v178 offset:28672
	ds_read_b64_tr_b16 v[206:207], v179 offset:30720
	ds_read_b128 v[140:143], v190 offset:32768
	s_waitcnt lgkmcnt(10)
	v_mfma_f32_32x32x16_bf16 v[48:63], v[144:147], v[216:219], v[48:63]
	v_exp_f32_e32 v88, v88
	v_exp_f32_e32 v89, v89
	v_exp_f32_e32 v90, v90
	ds_read_b64_tr_b16 v[246:247], v183 offset:28672
	ds_read_b64_tr_b16 v[248:249], v184 offset:30720
	ds_read_b128 v[144:147], v190 offset:40960
	v_mfma_f32_32x32x16_bf16 v[32:47], v[148:151], v[216:219], v[32:47]
	v_exp_f32_e32 v91, v91
	v_exp_f32_e32 v92, v92
	v_exp_f32_e32 v93, v93
	ds_read_b128 v[148:151], v191 offset:32768
	v_mfma_f32_32x32x16_bf16 v[16:31], v[152:155], v[216:219], v[16:31]
	v_exp_f32_e32 v94, v94
	v_exp_f32_e32 v95, v95
	v_cvt_pk_bf16_f32 v220, v88, v89
	v_cvt_pk_bf16_f32 v221, v90, v91
	ds_read_b128 v[152:155], v191 offset:40960
	v_mfma_f32_32x32x16_bf16 v[0:15], v[240:243], v[216:219], v[0:15]
	v_cvt_pk_bf16_f32 v222, v92, v93
	v_cvt_pk_bf16_f32 v223, v94, v95
	v_add_f32_e32 v187, v80, v187
	v_add_f32_e32 v192, v81, v192
	v_add_f32_e32 v193, v82, v193
	v_add_f32_e32 v194, v83, v194
	s_waitcnt lgkmcnt(3)
	v_mfma_f32_32x32x16_bf16 v[48:63], v[196:199], v[220:223], v[48:63]
	v_add_f32_e32 v187, v108, v187
	v_add_f32_e32 v192, v109, v192
	v_add_f32_e32 v193, v110, v193
	v_add_f32_e32 v194, v111, v194
	v_add_f32_e32 v187, v84, v187
	v_add_f32_e32 v192, v85, v192
	ds_read_b128 v[80:83], v188 offset:32768
	ds_read_b64_tr_b16 v[224:225], v174 offset:32768
	ds_read_b64_tr_b16 v[226:227], v175 offset:34816
	v_mfma_f32_32x32x16_bf16 v[32:47], v[200:203], v[220:223], v[32:47]
	v_add_f32_e32 v193, v86, v193
	v_add_f32_e32 v194, v87, v194
	v_add_f32_e32 v187, v88, v187
	v_add_f32_e32 v192, v89, v192
	v_add_f32_e32 v193, v90, v193
	v_add_f32_e32 v194, v91, v194
	ds_read_b64_tr_b16 v[228:229], v176 offset:32768
	ds_read_b64_tr_b16 v[230:231], v177 offset:34816
	v_mfma_f32_32x32x16_bf16 v[16:31], v[204:207], v[220:223], v[16:31]
	v_add_f32_e32 v187, v92, v187
	v_add_f32_e32 v192, v93, v192
	v_add_f32_e32 v193, v94, v193
	v_add_f32_e32 v194, v95, v194
	ds_read_b64_tr_b16 v[232:233], v178 offset:32768
	ds_read_b64_tr_b16 v[234:235], v179 offset:34816
	v_mfma_f32_32x32x16_bf16 v[0:15], v[246:249], v[220:223], v[0:15]
	ds_read_b64_tr_b16 v[236:237], v183 offset:32768
	ds_read_b64_tr_b16 v[238:239], v184 offset:34816
	s_add_i32 s10, s68, -2
	s_min_u32 s10, s10, s24
	s_lshl_b32 s10, s10, 15
	s_add_u32 s4, s20, s10
	s_addc_u32 s5, s21, 0
	s_waitcnt vmcnt(4)
	s_barrier
; __device__ __forceinline__ void attn_unit(LAS unsigned char* L, bf16_t* QKV, size_t rowbase, int S, int h, int qb, float lam, const float* subln, unsigned* kmax) {
;     ...
;     for (int t = 0; t < NT; t += 4) { TILE(t, 0); TILE(t + 1, 1); TILE(t + 2, 2); TILE(t + 3, 3); }
	s_mov_b32 m0, s46
	v_mfma_f32_32x32x16_bf16 v[96:111], v[132:135], v[116:119], v[64:79]
	global_load_lds_dwordx4 v163, s[4:5]
	s_mov_b32 m0, s47
	v_mfma_f32_32x32x16_bf16 v[96:111], v[140:143], v[120:123], v[96:111]
	global_load_lds_dwordx4 v254, s[4:5]
	s_mov_b32 m0, s51
	s_waitcnt lgkmcnt(10)
	v_mfma_f32_32x32x16_bf16 v[96:111], v[148:151], v[124:127], v[96:111]
	global_load_lds_dwordx4 v255, s[4:5]
	ds_read_b64_tr_b16 v[132:133], v176 offset:36864
	ds_read_b64_tr_b16 v[134:135], v177 offset:38912
	s_mov_b32 m0, s52
	s_waitcnt lgkmcnt(10)
	v_mfma_f32_32x32x16_bf16 v[96:111], v[80:83], v[112:115], v[96:111]
	global_load_lds_dwordx4 v253, s[4:5]
	ds_read_b64_tr_b16 v[140:141], v183 offset:36864
	ds_read_b64_tr_b16 v[142:143], v184 offset:38912
	v_mfma_f32_32x32x16_bf16 v[80:95], v[128:131], v[112:115], v[64:79]
	ds_read_b64_tr_b16 v[128:129], v174 offset:36864
	ds_read_b64_tr_b16 v[130:131], v175 offset:38912
	v_mfma_f32_32x32x16_bf16 v[80:95], v[136:139], v[116:119], v[80:95]
	s_nop 3
	v_mfma_f32_32x32x16_bf16 v[80:95], v[144:147], v[120:123], v[80:95]
	v_exp_f32_e32 v96, v96
	v_exp_f32_e32 v97, v97
	v_exp_f32_e32 v98, v98
	v_mfma_f32_32x32x16_bf16 v[80:95], v[152:155], v[124:127], v[80:95]
	v_exp_f32_e32 v99, v99
	v_exp_f32_e32 v100, v100
	v_exp_f32_e32 v101, v101
	v_exp_f32_e32 v102, v102
	v_exp_f32_e32 v103, v103
	v_cvt_pk_bf16_f32 v208, v96, v97
	v_cvt_pk_bf16_f32 v209, v98, v99
	v_cvt_pk_bf16_f32 v210, v100, v101
	v_cvt_pk_bf16_f32 v211, v102, v103
	v_exp_f32_e32 v104, v104
	v_exp_f32_e32 v105, v105
	s_waitcnt lgkmcnt(6)
	v_mfma_f32_32x32x16_bf16 v[48:63], v[224:227], v[208:211], v[48:63]
	v_exp_f32_e32 v106, v106
	v_exp_f32_e32 v107, v107
	v_exp_f32_e32 v108, v108
	ds_read_b64_tr_b16 v[136:137], v178 offset:36864
	ds_read_b64_tr_b16 v[138:139], v179 offset:38912
	v_mfma_f32_32x32x16_bf16 v[32:47], v[228:231], v[208:211], v[32:47]
	v_exp_f32_e32 v109, v109
	v_exp_f32_e32 v110, v110
	v_exp_f32_e32 v111, v111
	ds_read_b64_tr_b16 v[144:145], v174 offset:40960
	ds_read_b64_tr_b16 v[146:147], v175 offset:43008
	v_mfma_f32_32x32x16_bf16 v[16:31], v[232:235], v[208:211], v[16:31]
	v_cvt_pk_bf16_f32 v212, v104, v105
	v_cvt_pk_bf16_f32 v213, v106, v107
	v_cvt_pk_bf16_f32 v214, v108, v109
	v_cvt_pk_bf16_f32 v215, v110, v111
	v_add_f32_e32 v187, v96, v187
	v_add_f32_e32 v192, v97, v192
	ds_read_b64_tr_b16 v[148:149], v176 offset:40960
	ds_read_b64_tr_b16 v[150:151], v177 offset:43008
	v_mfma_f32_32x32x16_bf16 v[0:15], v[236:239], v[208:211], v[0:15]
	v_add_f32_e32 v193, v98, v193
	v_add_f32_e32 v194, v99, v194
	v_add_f32_e32 v187, v100, v187
	v_add_f32_e32 v192, v101, v192
	v_add_f32_e32 v193, v102, v193
	v_add_f32_e32 v194, v103, v194
	ds_read_b64_tr_b16 v[152:153], v178 offset:40960
	ds_read_b64_tr_b16 v[154:155], v179 offset:43008
	s_waitcnt lgkmcnt(6)
	v_mfma_f32_32x32x16_bf16 v[48:63], v[128:131], v[212:215], v[48:63]
	v_exp_f32_e32 v80, v80
	v_exp_f32_e32 v81, v81
	v_exp_f32_e32 v82, v82
	ds_read_b64_tr_b16 v[240:241], v183 offset:40960
	ds_read_b64_tr_b16 v[242:243], v184 offset:43008
	ds_read_b128 v[128:131], v188 offset:57344
	v_mfma_f32_32x32x16_bf16 v[32:47], v[132:135], v[212:215], v[32:47]
	v_exp_f32_e32 v83, v83
	v_exp_f32_e32 v84, v84
	v_exp_f32_e32 v85, v85
	ds_read_b64_tr_b16 v[196:197], v174 offset:45056
	ds_read_b64_tr_b16 v[198:199], v175 offset:47104
	ds_read_b128 v[132:135], v189 offset:49152
	v_mfma_f32_32x32x16_bf16 v[16:31], v[136:139], v[212:215], v[16:31]
	v_exp_f32_e32 v86, v86
	v_exp_f32_e32 v87, v87
	v_cvt_pk_bf16_f32 v216, v80, v81
	v_cvt_pk_bf16_f32 v217, v82, v83
	ds_read_b64_tr_b16 v[200:201], v176 offset:45056
	ds_read_b64_tr_b16 v[202:203], v177 offset:47104
	ds_read_b128 v[136:139], v189 offset:57344
	v_mfma_f32_32x32x16_bf16 v[0:15], v[140:143], v[212:215], v[0:15]
	v_cvt_pk_bf16_f32 v218, v84, v85
	v_cvt_pk_bf16_f32 v219, v86, v87
	v_add_f32_e32 v187, v104, v187
	v_add_f32_e32 v192, v105, v192
	v_add_f32_e32 v193, v106, v193
	v_add_f32_e32 v194, v107, v194
	s_waitcnt lgkmcnt(12)
	ds_read_b64_tr_b16 v[204:205], v178 offset:45056
	ds_read_b64_tr_b16 v[206:207], v179 offset:47104
	ds_read_b128 v[140:143], v190 offset:49152
	s_waitcnt lgkmcnt(10)
	v_mfma_f32_32x32x16_bf16 v[48:63], v[144:147], v[216:219], v[48:63]
	v_exp_f32_e32 v88, v88
	v_exp_f32_e32 v89, v89
	v_exp_f32_e32 v90, v90
	ds_read_b64_tr_b16 v[246:247], v183 offset:45056
	ds_read_b64_tr_b16 v[248:249], v184 offset:47104
	ds_read_b128 v[144:147], v190 offset:57344
	v_mfma_f32_32x32x16_bf16 v[32:47], v[148:151], v[216:219], v[32:47]
	v_exp_f32_e32 v91, v91
	v_exp_f32_e32 v92, v92
	v_exp_f32_e32 v93, v93
	ds_read_b128 v[148:151], v191 offset:49152
	v_mfma_f32_32x32x16_bf16 v[16:31], v[152:155], v[216:219], v[16:31]
	v_exp_f32_e32 v94, v94
	v_exp_f32_e32 v95, v95
	v_cvt_pk_bf16_f32 v220, v88, v89
	v_cvt_pk_bf16_f32 v221, v90, v91
	ds_read_b128 v[152:155], v191 offset:57344
	v_mfma_f32_32x32x16_bf16 v[0:15], v[240:243], v[216:219], v[0:15]
	v_cvt_pk_bf16_f32 v222, v92, v93
	v_cvt_pk_bf16_f32 v223, v94, v95
	v_add_f32_e32 v187, v80, v187
	v_add_f32_e32 v192, v81, v192
	v_add_f32_e32 v193, v82, v193
	v_add_f32_e32 v194, v83, v194
	s_waitcnt lgkmcnt(3)
	v_mfma_f32_32x32x16_bf16 v[48:63], v[196:199], v[220:223], v[48:63]
	v_add_f32_e32 v187, v108, v187
	v_add_f32_e32 v192, v109, v192
	v_add_f32_e32 v193, v110, v193
	v_add_f32_e32 v194, v111, v194
	v_add_f32_e32 v187, v84, v187
	v_add_f32_e32 v192, v85, v192
	ds_read_b128 v[80:83], v188 offset:49152
	ds_read_b64_tr_b16 v[224:225], v174 offset:49152
	ds_read_b64_tr_b16 v[226:227], v175 offset:51200
	v_mfma_f32_32x32x16_bf16 v[32:47], v[200:203], v[220:223], v[32:47]
	v_add_f32_e32 v193, v86, v193
	v_add_f32_e32 v194, v87, v194
	v_add_f32_e32 v187, v88, v187
	v_add_f32_e32 v192, v89, v192
	v_add_f32_e32 v193, v90, v193
	v_add_f32_e32 v194, v91, v194
	ds_read_b64_tr_b16 v[228:229], v176 offset:49152
	ds_read_b64_tr_b16 v[230:231], v177 offset:51200
	v_mfma_f32_32x32x16_bf16 v[16:31], v[204:207], v[220:223], v[16:31]
	v_add_f32_e32 v187, v92, v187
	v_add_f32_e32 v192, v93, v192
	v_add_f32_e32 v193, v94, v193
	v_add_f32_e32 v194, v95, v194
	ds_read_b64_tr_b16 v[232:233], v178 offset:49152
	ds_read_b64_tr_b16 v[234:235], v179 offset:51200
	v_mfma_f32_32x32x16_bf16 v[0:15], v[246:249], v[220:223], v[0:15]
	ds_read_b64_tr_b16 v[236:237], v183 offset:49152
	ds_read_b64_tr_b16 v[238:239], v184 offset:51200
	s_add_i32 s10, s68, -1
	s_min_u32 s10, s10, s24
	s_lshl_b32 s10, s10, 15
	s_add_u32 s22, s20, s10
	s_addc_u32 s23, s21, 0
	s_waitcnt vmcnt(4)
	s_barrier
; __device__ __forceinline__ void attn_unit(LAS unsigned char* L, bf16_t* QKV, size_t rowbase, int S, int h, int qb, float lam, const float* subln, unsigned* kmax) {
;     ...
;     for (int t = 0; t < NT; t += 4) { TILE(t, 0); TILE(t + 1, 1); TILE(t + 2, 2); TILE(t + 3, 3); }
	s_mov_b32 m0, s49
	v_mfma_f32_32x32x16_bf16 v[96:111], v[132:135], v[116:119], v[64:79]
	global_load_lds_dwordx4 v163, s[22:23]
	s_mov_b32 m0, s50
	v_mfma_f32_32x32x16_bf16 v[96:111], v[140:143], v[120:123], v[96:111]
	global_load_lds_dwordx4 v254, s[22:23]
	s_mov_b32 m0, s59
	s_waitcnt lgkmcnt(10)
	v_mfma_f32_32x32x16_bf16 v[96:111], v[148:151], v[124:127], v[96:111]
	global_load_lds_dwordx4 v255, s[22:23]
	ds_read_b64_tr_b16 v[132:133], v176 offset:53248
	ds_read_b64_tr_b16 v[134:135], v177 offset:55296
	s_mov_b32 m0, s61
	s_waitcnt lgkmcnt(10)
	v_mfma_f32_32x32x16_bf16 v[96:111], v[80:83], v[112:115], v[96:111]
	global_load_lds_dwordx4 v253, s[22:23]
	ds_read_b64_tr_b16 v[140:141], v183 offset:53248
	ds_read_b64_tr_b16 v[142:143], v184 offset:55296
	v_mfma_f32_32x32x16_bf16 v[80:95], v[128:131], v[112:115], v[64:79]
	ds_read_b64_tr_b16 v[128:129], v174 offset:53248
	ds_read_b64_tr_b16 v[130:131], v175 offset:55296
	v_mfma_f32_32x32x16_bf16 v[80:95], v[136:139], v[116:119], v[80:95]
	s_nop 3
	v_mfma_f32_32x32x16_bf16 v[80:95], v[144:147], v[120:123], v[80:95]
	v_exp_f32_e32 v96, v96
	v_exp_f32_e32 v97, v97
	v_exp_f32_e32 v98, v98
	v_mfma_f32_32x32x16_bf16 v[80:95], v[152:155], v[124:127], v[80:95]
	v_exp_f32_e32 v99, v99
	v_exp_f32_e32 v100, v100
	v_exp_f32_e32 v101, v101
	v_exp_f32_e32 v102, v102
	v_exp_f32_e32 v103, v103
	v_cvt_pk_bf16_f32 v208, v96, v97
	v_cvt_pk_bf16_f32 v209, v98, v99
	v_cvt_pk_bf16_f32 v210, v100, v101
	v_cvt_pk_bf16_f32 v211, v102, v103
	v_exp_f32_e32 v104, v104
	v_exp_f32_e32 v105, v105
	s_waitcnt lgkmcnt(6)
	v_mfma_f32_32x32x16_bf16 v[48:63], v[224:227], v[208:211], v[48:63]
	v_exp_f32_e32 v106, v106
	v_exp_f32_e32 v107, v107
	v_exp_f32_e32 v108, v108
	ds_read_b64_tr_b16 v[136:137], v178 offset:53248
	ds_read_b64_tr_b16 v[138:139], v179 offset:55296
	v_mfma_f32_32x32x16_bf16 v[32:47], v[228:231], v[208:211], v[32:47]
	v_exp_f32_e32 v109, v109
	v_exp_f32_e32 v110, v110
	v_exp_f32_e32 v111, v111
	ds_read_b64_tr_b16 v[144:145], v174 offset:57344
	ds_read_b64_tr_b16 v[146:147], v175 offset:59392
	v_mfma_f32_32x32x16_bf16 v[16:31], v[232:235], v[208:211], v[16:31]
	v_cvt_pk_bf16_f32 v212, v104, v105
	v_cvt_pk_bf16_f32 v213, v106, v107
	v_cvt_pk_bf16_f32 v214, v108, v109
	v_cvt_pk_bf16_f32 v215, v110, v111
	v_add_f32_e32 v187, v96, v187
	v_add_f32_e32 v192, v97, v192
	ds_read_b64_tr_b16 v[148:149], v176 offset:57344
	ds_read_b64_tr_b16 v[150:151], v177 offset:59392
	v_mfma_f32_32x32x16_bf16 v[0:15], v[236:239], v[208:211], v[0:15]
	v_add_f32_e32 v193, v98, v193
	v_add_f32_e32 v194, v99, v194
	v_add_f32_e32 v187, v100, v187
	v_add_f32_e32 v192, v101, v192
	v_add_f32_e32 v193, v102, v193
	v_add_f32_e32 v194, v103, v194
	ds_read_b64_tr_b16 v[152:153], v178 offset:57344
	ds_read_b64_tr_b16 v[154:155], v179 offset:59392
	s_waitcnt lgkmcnt(6)
	v_mfma_f32_32x32x16_bf16 v[48:63], v[128:131], v[212:215], v[48:63]
	v_exp_f32_e32 v80, v80
	v_exp_f32_e32 v81, v81
	v_exp_f32_e32 v82, v82
	ds_read_b64_tr_b16 v[240:241], v183 offset:57344
	ds_read_b64_tr_b16 v[242:243], v184 offset:59392
	ds_read_b128 v[128:131], v188 offset:8192
	v_mfma_f32_32x32x16_bf16 v[32:47], v[132:135], v[212:215], v[32:47]
	v_exp_f32_e32 v83, v83
	v_exp_f32_e32 v84, v84
	v_exp_f32_e32 v85, v85
	ds_read_b64_tr_b16 v[196:197], v174 offset:61440
	ds_read_b64_tr_b16 v[198:199], v175 offset:63488
	ds_read_b128 v[132:135], v189
	v_mfma_f32_32x32x16_bf16 v[16:31], v[136:139], v[212:215], v[16:31]
	v_exp_f32_e32 v86, v86
	v_exp_f32_e32 v87, v87
	v_cvt_pk_bf16_f32 v216, v80, v81
	v_cvt_pk_bf16_f32 v217, v82, v83
	ds_read_b64_tr_b16 v[200:201], v176 offset:61440
	ds_read_b64_tr_b16 v[202:203], v177 offset:63488
	ds_read_b128 v[136:139], v189 offset:8192
	v_mfma_f32_32x32x16_bf16 v[0:15], v[140:143], v[212:215], v[0:15]
	v_cvt_pk_bf16_f32 v218, v84, v85
	v_cvt_pk_bf16_f32 v219, v86, v87
	v_add_f32_e32 v187, v104, v187
	v_add_f32_e32 v192, v105, v192
	v_add_f32_e32 v193, v106, v193
	v_add_f32_e32 v194, v107, v194
	s_waitcnt lgkmcnt(12)
	ds_read_b64_tr_b16 v[204:205], v178 offset:61440
	ds_read_b64_tr_b16 v[206:207], v179 offset:63488
	ds_read_b128 v[140:143], v190
	s_waitcnt lgkmcnt(10)
	v_mfma_f32_32x32x16_bf16 v[48:63], v[144:147], v[216:219], v[48:63]
	v_exp_f32_e32 v88, v88
	v_exp_f32_e32 v89, v89
	v_exp_f32_e32 v90, v90
	ds_read_b64_tr_b16 v[246:247], v183 offset:61440
	ds_read_b64_tr_b16 v[248:249], v184 offset:63488
	ds_read_b128 v[144:147], v190 offset:8192
	v_mfma_f32_32x32x16_bf16 v[32:47], v[148:151], v[216:219], v[32:47]
	v_exp_f32_e32 v91, v91
	v_exp_f32_e32 v92, v92
	v_exp_f32_e32 v93, v93
	ds_read_b128 v[148:151], v191
	v_mfma_f32_32x32x16_bf16 v[16:31], v[152:155], v[216:219], v[16:31]
	v_exp_f32_e32 v94, v94
	v_exp_f32_e32 v95, v95
	v_cvt_pk_bf16_f32 v220, v88, v89
	v_cvt_pk_bf16_f32 v221, v90, v91
	ds_read_b128 v[152:155], v191 offset:8192
	v_mfma_f32_32x32x16_bf16 v[0:15], v[240:243], v[216:219], v[0:15]
	v_cvt_pk_bf16_f32 v222, v92, v93
	v_cvt_pk_bf16_f32 v223, v94, v95
	v_add_f32_e32 v187, v80, v187
	v_add_f32_e32 v192, v81, v192
	v_add_f32_e32 v193, v82, v193
	v_add_f32_e32 v194, v83, v194
	s_waitcnt lgkmcnt(3)
	v_mfma_f32_32x32x16_bf16 v[48:63], v[196:199], v[220:223], v[48:63]
	v_add_f32_e32 v187, v108, v187
	v_add_f32_e32 v192, v109, v192
	v_add_f32_e32 v193, v110, v193
	v_add_f32_e32 v194, v111, v194
	v_add_f32_e32 v187, v84, v187
	v_add_f32_e32 v192, v85, v192
	ds_read_b128 v[80:83], v188
	ds_read_b64_tr_b16 v[224:225], v174
	ds_read_b64_tr_b16 v[226:227], v175 offset:2048
	v_mfma_f32_32x32x16_bf16 v[32:47], v[200:203], v[220:223], v[32:47]
	v_add_f32_e32 v193, v86, v193
	v_add_f32_e32 v194, v87, v194
	v_add_f32_e32 v187, v88, v187
	v_add_f32_e32 v192, v89, v192
	v_add_f32_e32 v193, v90, v193
	v_add_f32_e32 v194, v91, v194
	ds_read_b64_tr_b16 v[228:229], v176
	ds_read_b64_tr_b16 v[230:231], v177 offset:2048
	v_mfma_f32_32x32x16_bf16 v[16:31], v[204:207], v[220:223], v[16:31]
	v_add_f32_e32 v187, v92, v187
	v_add_f32_e32 v192, v93, v192
	v_add_f32_e32 v193, v94, v193
	v_add_f32_e32 v194, v95, v194
	ds_read_b64_tr_b16 v[232:233], v178
	ds_read_b64_tr_b16 v[234:235], v179 offset:2048
	v_mfma_f32_32x32x16_bf16 v[0:15], v[246:249], v[220:223], v[0:15]
	ds_read_b64_tr_b16 v[236:237], v183
	ds_read_b64_tr_b16 v[238:239], v184 offset:2048
	s_min_u32 s10, s68, s24
	s_lshl_b32 s10, s10, 15
	s_add_u32 s4, s20, s10
	s_addc_u32 s5, s21, 0
	s_waitcnt vmcnt(4)
	s_add_i32 s68, s68, 4
	s_cmp_ge_u32 s69, s42
	s_barrier
; #define LAS __attribute__((address_space(3)))
; #define DMA_WAIT_BAR() do { asm volatile("s_waitcnt vmcnt(0)" ::: "memory"); __syncthreads(); } while (0)
; __device__ __forceinline__ void attn_unit(LAS unsigned char* L, bf16_t* QKV, size_t rowbase, int S, int h, int qb, float lam, const float* subln, unsigned* kmax) {
;     ...
;     DMA_WAIT_BAR();
;     ...
;     lsum = (lsum + lsb) + (lsc + lsd);
;     const float inv = 1.f / (lsum + __shfl_xor(lsum, 32));
;     LAS float* X = (LAS float*)L;
;     const int xo = (32 * qblk + r32) * AXP + 4 * hi;
;     if (hd == 1) { const float sc = inv * lam;
; #pragma unroll
;         for (int d = 0; d < 4; ++d)
; #pragma unroll
;             for (int rg = 0; rg < 4; ++rg) *(LAS f32x4*)(X + xo + 32 * d + 8 * rg) = (f32x4){o[d][4 * rg] * sc, o[d][4 * rg + 1] * sc, o[d][4 * rg + 2] * sc, o[d][4 * rg + 3] * sc}; }
	s_cbranch_scc0 .LBB0_927
	v_add_f32_e32 v64, v187, v192
	v_add_f32_e32 v65, v193, v194
	v_add_f32_e32 v64, v64, v65
	ds_bpermute_b32 v65, v156, v64
	s_waitcnt vmcnt(0)
	s_cmp_eq_u32 s40, 1
	s_waitcnt lgkmcnt(0)
	s_barrier
	v_add_f32_e32 v64, v64, v65
	v_div_scale_f32 v65, s[4:5], v64, v64, 1.0
	v_rcp_f32_e32 v66, v65
	s_nop 0
	v_fma_f32 v67, -v65, v66, 1.0
	v_fmac_f32_e32 v66, v67, v66
	v_div_scale_f32 v67, vcc, 1.0, v64, 1.0
	v_mul_f32_e32 v68, v67, v66
	v_fma_f32 v69, -v65, v68, v67
	v_fmac_f32_e32 v68, v69, v66
	v_fma_f32 v65, -v65, v68, v67
	v_div_fmas_f32 v65, v65, v66, v68
	v_div_fixup_f32 v66, v65, v64, 1.0
	v_or_b32_e32 v64, s41, v182
	v_mad_u32_u24 v64, v64, s38, v158
	v_lshl_add_u32 v64, v64, 2, 0
	s_cbranch_scc0 .LBB0_930
	v_mul_f32_e32 v72, v159, v66
	v_pk_mul_f32 v[68:69], v[48:49], v[72:73] op_sel_hi:[1,0]
	v_pk_mul_f32 v[70:71], v[50:51], v[72:73] op_sel_hi:[1,0]
	ds_write_b128 v64, v[68:71]
	v_pk_mul_f32 v[68:69], v[52:53], v[72:73] op_sel_hi:[1,0]
	v_pk_mul_f32 v[70:71], v[54:55], v[72:73] op_sel_hi:[1,0]
	ds_write_b128 v64, v[68:71] offset:32
	v_pk_mul_f32 v[68:69], v[56:57], v[72:73] op_sel_hi:[1,0]
	v_pk_mul_f32 v[70:71], v[58:59], v[72:73] op_sel_hi:[1,0]
	ds_write_b128 v64, v[68:71] offset:64
	v_pk_mul_f32 v[68:69], v[60:61], v[72:73] op_sel_hi:[1,0]
	v_pk_mul_f32 v[70:71], v[62:63], v[72:73] op_sel_hi:[1,0]
	ds_write_b128 v64, v[68:71] offset:96
	v_pk_mul_f32 v[68:69], v[32:33], v[72:73] op_sel_hi:[1,0]
	v_pk_mul_f32 v[70:71], v[34:35], v[72:73] op_sel_hi:[1,0]
	ds_write_b128 v64, v[68:71] offset:128
	v_pk_mul_f32 v[68:69], v[36:37], v[72:73] op_sel_hi:[1,0]
	v_pk_mul_f32 v[70:71], v[38:39], v[72:73] op_sel_hi:[1,0]
	ds_write_b128 v64, v[68:71] offset:160
	v_pk_mul_f32 v[68:69], v[40:41], v[72:73] op_sel_hi:[1,0]
	v_pk_mul_f32 v[70:71], v[42:43], v[72:73] op_sel_hi:[1,0]
	ds_write_b128 v64, v[68:71] offset:192
	v_pk_mul_f32 v[68:69], v[44:45], v[72:73] op_sel_hi:[1,0]
	v_pk_mul_f32 v[70:71], v[46:47], v[72:73] op_sel_hi:[1,0]
	ds_write_b128 v64, v[68:71] offset:224
	v_pk_mul_f32 v[68:69], v[16:17], v[72:73] op_sel_hi:[1,0]
	v_pk_mul_f32 v[70:71], v[18:19], v[72:73] op_sel_hi:[1,0]
	ds_write_b128 v64, v[68:71] offset:256
	v_pk_mul_f32 v[68:69], v[20:21], v[72:73] op_sel_hi:[1,0]
	v_pk_mul_f32 v[70:71], v[22:23], v[72:73] op_sel_hi:[1,0]
	ds_write_b128 v64, v[68:71] offset:288
	v_pk_mul_f32 v[68:69], v[24:25], v[72:73] op_sel_hi:[1,0]
	v_pk_mul_f32 v[70:71], v[26:27], v[72:73] op_sel_hi:[1,0]
	ds_write_b128 v64, v[68:71] offset:320
	v_pk_mul_f32 v[68:69], v[28:29], v[72:73] op_sel_hi:[1,0]
	v_pk_mul_f32 v[70:71], v[30:31], v[72:73] op_sel_hi:[1,0]
	ds_write_b128 v64, v[68:71] offset:352
	v_pk_mul_f32 v[68:69], v[0:1], v[72:73] op_sel_hi:[1,0]
	v_pk_mul_f32 v[70:71], v[2:3], v[72:73] op_sel_hi:[1,0]
	ds_write_b128 v64, v[68:71] offset:384
	v_pk_mul_f32 v[68:69], v[4:5], v[72:73] op_sel_hi:[1,0]
	v_pk_mul_f32 v[70:71], v[6:7], v[72:73] op_sel_hi:[1,0]
	ds_write_b128 v64, v[68:71] offset:416
	v_pk_mul_f32 v[68:69], v[8:9], v[72:73] op_sel_hi:[1,0]
	v_pk_mul_f32 v[70:71], v[10:11], v[72:73] op_sel_hi:[1,0]
	ds_write_b128 v64, v[68:71] offset:448
	v_pk_mul_f32 v[68:69], v[12:13], v[72:73] op_sel_hi:[1,0]
	v_pk_mul_f32 v[70:71], v[14:15], v[72:73] op_sel_hi:[1,0]
	ds_write_b128 v64, v[68:71] offset:480
